# GDN scan start: chunk-0 staging loads batched (seven loads in flight instead of seven serialized round trips)
# baseline (speedup 1.0000x reference)
; #define GAS __attribute__((address_space(1)))
; #define LAS __attribute__((address_space(3)))
; #define BAR_RAW() do { asm volatile("s_waitcnt lgkmcnt(0)" ::: "memory"); __builtin_amdgcn_s_barrier(); asm volatile("" ::: "memory"); } while (0)
; DI void copy_g2l(LAS unsigned char* dst, const unsigned char* src, int bytes, int tid) {
;     for (int o = tid * 16; o < bytes; o += 512 * 16) *(LAS v4u*)(dst + o) = *(const GAS v4u*)(src + o);
; }
;     ...
;     copy_g2l(L, gw, 16384, tid); copy_g2l(L + 16384, gq, 16384, tid); copy_g2l(L + 32768, gk, 16384, tid); copy_g2l(L + 49152, ga, 8192, tid);
;     BAR_RAW();
;     ...
;         } else {
;             const int hn = tid - 384, nt_t = hn >> 1, nt_c0 = 64 * (hn & 1);
;             bf16* MIX = (bf16*)(F.ws + WS_MIX);
;             const bf16* zbase = (const bf16*)(F.ws + WS_GZ) + ((size_t)bh * SEQ + nt_t) * 128 + nt_c0;
;             v4u za[8], zb[8];
; #pragma unroll
;             for (int i = 0; i < 8; ++i) { za[i] = (v4u){0u, 0u, 0u, 0u}; zb[i] = (v4u){0u, 0u, 0u, 0u}; }
.LBB0_960:
	s_andn2_b64 vcc, exec, s[0:1]
	s_cbranch_vccnz .LBB0_990
	s_waitcnt vmcnt(0)
	v_mbcnt_lo_u32_b32 v0, -1, 0
	v_mbcnt_hi_u32_b32 v0, -1, v0
	s_mov_b64 s[0:1], s[86:87]
	v_add_u32_e32 v101, s81, v0
	s_mov_b64 s[30:31], s[84:85]
	s_mov_b64 s[30:31], s[82:83]
	v_lshlrev_b32_e32 v0, 4, v101
	s_movk_i32 s30, 0x400
	v_readfirstlane_b32 s2, v101
	v_cmp_gt_i32_e32 vcc, s30, v101
	s_waitcnt lgkmcnt(0)
	v_ashrrev_i32_e32 v1, 31, v0
	v_add_u32_e32 v4, 0xffffe000, v0
	s_and_saveexec_b64 s[30:31], vcc
	s_mov_b64 s[44:45], 0x2000
	s_cbranch_execz .LBB0_968
	v_readlane_b32 s36, v254, 39
	s_add_u32 s38, s0, s36
	v_readlane_b32 s36, v254, 40
	s_addc_u32 s39, s1, s36
	global_load_dwordx4 v[8:11], v0, s[38:39]
	s_add_u32 s40, s38, 0x2000
	s_addc_u32 s41, s39, 0
	global_load_dwordx4 v[12:15], v0, s[40:41]
	v_readlane_b32 s36, v254, 41
	s_add_u32 s38, s0, s36
	v_readlane_b32 s36, v254, 42
	s_addc_u32 s39, s1, s36
	global_load_dwordx4 v[16:19], v0, s[38:39]
	s_add_u32 s40, s38, 0x2000
	s_addc_u32 s41, s39, 0
	global_load_dwordx4 v[20:23], v0, s[40:41]
	v_readlane_b32 s36, v254, 43
	s_add_u32 s38, s0, s36
	v_readlane_b32 s36, v254, 46
	s_addc_u32 s39, s1, s36
	global_load_dwordx4 v[24:27], v0, s[38:39]
	s_add_u32 s40, s38, 0x2000
	s_addc_u32 s41, s39, 0
	global_load_dwordx4 v[28:31], v0, s[40:41]
	v_readlane_b32 s36, v254, 47
	s_add_u32 s38, s0, s36
	v_readlane_b32 s36, v254, 50
	s_addc_u32 s39, s1, s36
	global_load_dwordx4 v[32:35], v0, s[38:39]
	s_waitcnt vmcnt(0)
	ds_write_b128 v0, v[8:11]
	ds_write_b128 v0, v[12:15] offset:8192
	ds_write_b128 v0, v[16:19] offset:16384
	ds_write_b128 v0, v[20:23] offset:24576
	ds_write_b128 v0, v[24:27] offset:32768
	ds_write_b128 v0, v[28:31] offset:40960
	ds_write_b128 v0, v[32:35] offset:49152
.LBB0_968:
.LBB0_971:
	s_or_b64 exec, exec, s[30:31]
	s_waitcnt lgkmcnt(0)
	s_barrier
	s_ashr_i32 s36, s2, 6
	v_and_b32_e32 v146, 63, v101
	s_cmp_gt_i32 s36, 3
	s_mov_b64 s[30:31], -1
	s_cbranch_scc0 .LBB0_986
	s_cmp_gt_u32 s36, 5
	s_cbranch_scc0 .LBB0_980
	v_add_u32_e32 v0, 0xfffffe80, v101
	v_ashrrev_i32_e32 v0, 1, v0
	v_lshlrev_b32_e32 v1, 6, v101
	v_readlane_b32 s30, v254, 44
	v_and_b32_e32 v4, 64, v1
	v_ashrrev_i32_e32 v1, 31, v0
	v_readlane_b32 s31, v254, 45
	s_add_u32 s30, s0, s30
	v_lshlrev_b64 v[2:3], 8, v[0:1]
	s_addc_u32 s31, s1, s31
	v_lshlrev_b32_e32 v96, 1, v4
	v_lshl_add_u64 v[98:99], s[30:31], 0, v[2:3]
	v_lshl_add_u64 v[2:3], v[98:99], 0, v[96:97]
	s_mov_b64 s[30:31], 0x45060000
	v_lshl_add_u64 v[134:135], v[2:3], 0, s[30:31]
	v_readlane_b32 s30, v253, 52
	v_readlane_b32 s31, v253, 53
	s_movk_i32 s2, 0x210
	v_readlane_b32 s38, v255, 9
	v_lshl_add_u64 v[136:137], v[0:1], 0, s[30:31]
	v_mul_lo_u32 v0, v0, s2
	s_add_i32 s2, 0, 0x1c000
	v_readlane_b32 s39, v255, 10
	s_add_u32 s30, s0, s38
	v_lshlrev_b32_e32 v1, 2, v4
	s_addc_u32 s31, s1, s39
	v_add3_u32 v147, s2, v0, v1
	v_lshl_add_u64 v[0:1], s[30:31], 0, v[96:97]
	s_mov_b64 s[30:31], 0x39d80000
	v_lshl_add_u64 v[138:139], v[0:1], 0, s[30:31]
	v_and_b32_e32 v0, 1, v101
	s_add_u32 s30, s0, s38
	v_lshlrev_b32_e32 v140, 7, v0
	s_addc_u32 s31, s1, s39
	v_lshlrev_b64 v[0:1], 12, v[136:137]
	v_mov_b32_e32 v141, v97
	v_lshl_add_u64 v[142:143], s[30:31], 0, v[0:1]
	s_mov_b32 s38, 0
	v_not_b32_e32 v96, 63
	v_mov_b32_e32 v0, 0
	v_mov_b32_e32 v1, 0
	v_mov_b32_e32 v2, 0
	v_mov_b32_e32 v3, 0
	v_mov_b32_e32 v4, 0
	v_mov_b32_e32 v5, 0
	v_mov_b32_e32 v6, 0
	v_mov_b32_e32 v7, 0
	v_mov_b32_e32 v8, 0
	v_mov_b32_e32 v9, 0
	v_mov_b32_e32 v10, 0
	v_mov_b32_e32 v11, 0
	v_mov_b32_e32 v12, 0
	v_mov_b32_e32 v13, 0
	v_mov_b32_e32 v14, 0
	v_mov_b32_e32 v15, 0
	v_mov_b32_e32 v16, 0
	v_mov_b32_e32 v17, 0
	v_mov_b32_e32 v18, 0
	v_mov_b32_e32 v19, 0
	v_mov_b32_e32 v20, 0
	v_mov_b32_e32 v21, 0
	v_mov_b32_e32 v22, 0
	v_mov_b32_e32 v23, 0
	v_mov_b32_e32 v28, 0
	v_mov_b32_e32 v29, 0
	v_mov_b32_e32 v30, 0
	v_mov_b32_e32 v31, 0
	v_mov_b32_e32 v36, 0
	v_mov_b32_e32 v37, 0
	v_mov_b32_e32 v38, 0
	v_mov_b32_e32 v39, 0
	v_readlane_b32 s100, v254, 44
	v_readlane_b32 s101, v254, 45
	v_readlane_b32 s44, v254, 48
	s_add_u32 s100, s0, s100
	s_addc_u32 s101, s1, s101
	s_add_u32 s100, s100, 0x3fe50000
	s_addc_u32 s101, s101, 0
	v_readlane_b32 s41, v254, 44
	s_sub_i32 s46, s81, 0x180
	s_lshl_b32 s46, s46, 5
	s_sub_i32 s44, s44, s41
	s_add_i32 s44, s44, 0x2401000
	v_lshlrev_b32_e32 v160, 4, v146
	v_add_u32_e32 v160, s46, v160
	v_add_u32_e32 v161, s44, v160
	v_add_u32_e32 v160, 0x2000, v160
	s_branch .LBB0_975
